# down-phase meta-row tail units moved to the workgroups that finish the fused up+down pair earliest
# speedup vs baseline: 1.0189x; 1.0189x over previous
.LBB0_907:
	s_andn2_b64 vcc, exec, s[14:15]
	s_cbranch_vccnz .LBB0_927
	s_add_i32 s0, s55, 0x80
	s_ashr_i32 s1, s0, 31
	s_lshr_b32 s1, s1, 24
	s_add_i32 s1, s0, s1
	s_and_b32 s1, s1, 0xffffff00
	s_sub_i32 s15, s0, s1
	s_cmp_gt_i32 s15, 15
	v_mbcnt_lo_u32_b32 v1, -1, 0
	v_mbcnt_hi_u32_b32 v1, -1, v1
	s_cbranch_scc1 .LBB0_927
	s_waitcnt lgkmcnt(0)
	v_readlane_b32 s16, v255, 11
	s_mov_b32 s17, 0
	s_cmp_eq_u32 s16, 2
	s_cselect_b32 s17, 88, s17
	s_cmp_eq_u32 s16, 9
	s_cselect_b32 s17, 176, s17
	s_cmp_eq_u32 s16, 11
	s_cselect_b32 s17, 264, s17
	s_cmp_eq_u32 s17, 0
	s_cbranch_scc1 .Ltail_skip
	s_cmp_lg_u32 s86, 0
	s_cbranch_scc1 .Ltail_bar
	v_mov_b32_e32 v2, 0x3d00
	s_mov_b32 s18, 0
